# adaLN GEMV prefetch ring 16 -> 32 loads in flight
# speedup vs baseline: 1.0012x; 1.0012x over previous
.LBB0_537:
	s_or_b64 exec, exec, s[2:3]
	s_mul_hi_i32 s2, s6, 0x2aaaaaab
	s_lshr_b32 s3, s2, 31
	s_ashr_i32 s4, s2, 3
	s_add_i32 s4, s4, s3
	s_mul_i32 s2, s4, 48
	s_sub_i32 s2, s6, s2
	v_lshl_or_b32 v8, s2, 6, v0
	v_ashrrev_i32_e32 v9, 31, v8
	v_lshlrev_b64 v[10:11], 2, v[8:9]
	v_mad_i64_i32 v[10:11], s[2:3], s4, v211, v[10:11]
	v_mov_b32_e32 v12, 0
	v_lshl_add_u64 v[10:11], v[6:7], 0, v[10:11]
	s_mov_b64 s[2:3], 0
	v_mov_b32_e32 v25, v3
	v_mov_b32_e32 v13, v12
	v_mov_b32_e32 v18, v12
	v_mov_b32_e32 v19, v12
	v_mov_b32_e32 v16, v12
	v_mov_b32_e32 v17, v12
	v_mov_b32_e32 v14, v12
	v_mov_b32_e32 v15, v12
	s_waitcnt lgkmcnt(0)
	s_barrier
	v_mov_b32_e32 v158, 0x3000
	v_mov_b32_e32 v159, 0
	v_mov_b32_e32 v160, 0x6000
	v_mov_b32_e32 v161, 0
	v_mov_b32_e32 v162, 0x9000
	v_mov_b32_e32 v163, 0
	v_mov_b32_e32 v164, 0xc000
	v_mov_b32_e32 v165, 0
	v_mov_b32_e32 v166, v10
	v_mov_b32_e32 v167, v11
	global_load_dword v66, v[166:167], off
	v_lshl_add_u64 v[168:169], v[166:167], 0, v[158:159]
	v_lshl_add_u64 v[170:171], v[166:167], 0, v[160:161]
	v_lshl_add_u64 v[172:173], v[166:167], 0, v[162:163]
	global_load_dword v67, v[168:169], off
	global_load_dword v68, v[170:171], off
	global_load_dword v69, v[172:173], off
	v_lshl_add_u64 v[166:167], v[166:167], 0, v[164:165]
	global_load_dword v70, v[166:167], off
	v_lshl_add_u64 v[168:169], v[166:167], 0, v[158:159]
	v_lshl_add_u64 v[170:171], v[166:167], 0, v[160:161]
	v_lshl_add_u64 v[172:173], v[166:167], 0, v[162:163]
	global_load_dword v71, v[168:169], off
	global_load_dword v72, v[170:171], off
	global_load_dword v73, v[172:173], off
	v_lshl_add_u64 v[166:167], v[166:167], 0, v[164:165]
	global_load_dword v74, v[166:167], off
	v_lshl_add_u64 v[168:169], v[166:167], 0, v[158:159]
	v_lshl_add_u64 v[170:171], v[166:167], 0, v[160:161]
	v_lshl_add_u64 v[172:173], v[166:167], 0, v[162:163]
	global_load_dword v75, v[168:169], off
	global_load_dword v76, v[170:171], off
	global_load_dword v77, v[172:173], off
	v_lshl_add_u64 v[166:167], v[166:167], 0, v[164:165]
	global_load_dword v78, v[166:167], off
	v_lshl_add_u64 v[168:169], v[166:167], 0, v[158:159]
	v_lshl_add_u64 v[170:171], v[166:167], 0, v[160:161]
	v_lshl_add_u64 v[172:173], v[166:167], 0, v[162:163]
	global_load_dword v79, v[168:169], off
	global_load_dword v80, v[170:171], off
	global_load_dword v81, v[172:173], off
	v_lshl_add_u64 v[166:167], v[166:167], 0, v[164:165]
	global_load_dword v82, v[166:167], off
	v_lshl_add_u64 v[168:169], v[166:167], 0, v[158:159]
	v_lshl_add_u64 v[170:171], v[166:167], 0, v[160:161]
	v_lshl_add_u64 v[172:173], v[166:167], 0, v[162:163]
	global_load_dword v83, v[168:169], off
	global_load_dword v84, v[170:171], off
	global_load_dword v85, v[172:173], off
	v_lshl_add_u64 v[166:167], v[166:167], 0, v[164:165]
	global_load_dword v86, v[166:167], off
	v_lshl_add_u64 v[168:169], v[166:167], 0, v[158:159]
	v_lshl_add_u64 v[170:171], v[166:167], 0, v[160:161]
	v_lshl_add_u64 v[172:173], v[166:167], 0, v[162:163]
	global_load_dword v87, v[168:169], off
	global_load_dword v88, v[170:171], off
	global_load_dword v89, v[172:173], off
	v_lshl_add_u64 v[166:167], v[166:167], 0, v[164:165]
	global_load_dword v90, v[166:167], off
	v_lshl_add_u64 v[168:169], v[166:167], 0, v[158:159]
	v_lshl_add_u64 v[170:171], v[166:167], 0, v[160:161]
	v_lshl_add_u64 v[172:173], v[166:167], 0, v[162:163]
	global_load_dword v91, v[168:169], off
	global_load_dword v92, v[170:171], off
	global_load_dword v93, v[172:173], off
	v_lshl_add_u64 v[166:167], v[166:167], 0, v[164:165]
	global_load_dword v94, v[166:167], off
	v_lshl_add_u64 v[168:169], v[166:167], 0, v[158:159]
	v_lshl_add_u64 v[170:171], v[166:167], 0, v[160:161]
	v_lshl_add_u64 v[172:173], v[166:167], 0, v[162:163]
	global_load_dword v95, v[168:169], off
	global_load_dword v96, v[170:171], off
	global_load_dword v97, v[172:173], off
	v_lshl_add_u64 v[166:167], v[166:167], 0, v[164:165]
	s_mov_b32 s2, 7
.Lada_loop:
	ds_read_b128 v[26:29], v25
	ds_read_b128 v[30:33], v25 offset:4096
	ds_read_b128 v[34:37], v25 offset:8192
	ds_read_b128 v[38:41], v25 offset:12288
	ds_read_b128 v[42:45], v25 offset:16384
	ds_read_b128 v[46:49], v25 offset:20480
	ds_read_b128 v[50:53], v25 offset:24576
	ds_read_b128 v[54:57], v25 offset:28672
	v_add_u32_e32 v25, 16, v25
	s_waitcnt vmcnt(28)
	s_waitcnt lgkmcnt(0)
	v_fmac_f32_e32 v18, v66, v26
	v_fmac_f32_e32 v19, v66, v30
	v_fmac_f32_e32 v16, v66, v34
	v_fmac_f32_e32 v17, v66, v38
	v_fmac_f32_e32 v14, v66, v42
	v_fmac_f32_e32 v15, v66, v46
	v_fmac_f32_e32 v12, v66, v50
	v_fmac_f32_e32 v13, v66, v54
	v_fmac_f32_e32 v18, v67, v27
	v_fmac_f32_e32 v19, v67, v31
	v_fmac_f32_e32 v16, v67, v35
	v_fmac_f32_e32 v17, v67, v39
	v_fmac_f32_e32 v14, v67, v43
	v_fmac_f32_e32 v15, v67, v47
	v_fmac_f32_e32 v12, v67, v51
	v_fmac_f32_e32 v13, v67, v55
	v_fmac_f32_e32 v18, v68, v28
	v_fmac_f32_e32 v19, v68, v32
	v_fmac_f32_e32 v16, v68, v36
	v_fmac_f32_e32 v17, v68, v40
	v_fmac_f32_e32 v14, v68, v44
	v_fmac_f32_e32 v15, v68, v48
	v_fmac_f32_e32 v12, v68, v52
	v_fmac_f32_e32 v13, v68, v56
	v_fmac_f32_e32 v18, v69, v29
	v_fmac_f32_e32 v19, v69, v33
	v_fmac_f32_e32 v16, v69, v37
	v_fmac_f32_e32 v17, v69, v41
	v_fmac_f32_e32 v14, v69, v45
	v_fmac_f32_e32 v15, v69, v49
	v_fmac_f32_e32 v12, v69, v53
	v_fmac_f32_e32 v13, v69, v57
	global_load_dword v66, v[166:167], off
	v_lshl_add_u64 v[168:169], v[166:167], 0, v[158:159]
	v_lshl_add_u64 v[170:171], v[166:167], 0, v[160:161]
	v_lshl_add_u64 v[172:173], v[166:167], 0, v[162:163]
	global_load_dword v67, v[168:169], off
	global_load_dword v68, v[170:171], off
	global_load_dword v69, v[172:173], off
	v_lshl_add_u64 v[166:167], v[166:167], 0, v[164:165]
	ds_read_b128 v[26:29], v25
	ds_read_b128 v[30:33], v25 offset:4096
	ds_read_b128 v[34:37], v25 offset:8192
	ds_read_b128 v[38:41], v25 offset:12288
	ds_read_b128 v[42:45], v25 offset:16384
	ds_read_b128 v[46:49], v25 offset:20480
	ds_read_b128 v[50:53], v25 offset:24576
	ds_read_b128 v[54:57], v25 offset:28672
	v_add_u32_e32 v25, 16, v25
	s_waitcnt vmcnt(28)
	s_waitcnt lgkmcnt(0)
	v_fmac_f32_e32 v18, v70, v26
	v_fmac_f32_e32 v19, v70, v30
	v_fmac_f32_e32 v16, v70, v34
	v_fmac_f32_e32 v17, v70, v38
	v_fmac_f32_e32 v14, v70, v42
	v_fmac_f32_e32 v15, v70, v46
	v_fmac_f32_e32 v12, v70, v50
	v_fmac_f32_e32 v13, v70, v54
	v_fmac_f32_e32 v18, v71, v27
	v_fmac_f32_e32 v19, v71, v31
	v_fmac_f32_e32 v16, v71, v35
	v_fmac_f32_e32 v17, v71, v39
	v_fmac_f32_e32 v14, v71, v43
	v_fmac_f32_e32 v15, v71, v47
	v_fmac_f32_e32 v12, v71, v51
	v_fmac_f32_e32 v13, v71, v55
	v_fmac_f32_e32 v18, v72, v28
	v_fmac_f32_e32 v19, v72, v32
	v_fmac_f32_e32 v16, v72, v36
	v_fmac_f32_e32 v17, v72, v40
	v_fmac_f32_e32 v14, v72, v44
	v_fmac_f32_e32 v15, v72, v48
	v_fmac_f32_e32 v12, v72, v52
	v_fmac_f32_e32 v13, v72, v56
	v_fmac_f32_e32 v18, v73, v29
	v_fmac_f32_e32 v19, v73, v33
	v_fmac_f32_e32 v16, v73, v37
	v_fmac_f32_e32 v17, v73, v41
	v_fmac_f32_e32 v14, v73, v45
	v_fmac_f32_e32 v15, v73, v49
	v_fmac_f32_e32 v12, v73, v53
	v_fmac_f32_e32 v13, v73, v57
	global_load_dword v70, v[166:167], off
	v_lshl_add_u64 v[168:169], v[166:167], 0, v[158:159]
	v_lshl_add_u64 v[170:171], v[166:167], 0, v[160:161]
	v_lshl_add_u64 v[172:173], v[166:167], 0, v[162:163]
	global_load_dword v71, v[168:169], off
	global_load_dword v72, v[170:171], off
	global_load_dword v73, v[172:173], off
	v_lshl_add_u64 v[166:167], v[166:167], 0, v[164:165]
	ds_read_b128 v[26:29], v25
	ds_read_b128 v[30:33], v25 offset:4096
	ds_read_b128 v[34:37], v25 offset:8192
	ds_read_b128 v[38:41], v25 offset:12288
	ds_read_b128 v[42:45], v25 offset:16384
	ds_read_b128 v[46:49], v25 offset:20480
	ds_read_b128 v[50:53], v25 offset:24576
	ds_read_b128 v[54:57], v25 offset:28672
	v_add_u32_e32 v25, 16, v25
	s_waitcnt vmcnt(28)
	s_waitcnt lgkmcnt(0)
	v_fmac_f32_e32 v18, v74, v26
	v_fmac_f32_e32 v19, v74, v30
	v_fmac_f32_e32 v16, v74, v34
	v_fmac_f32_e32 v17, v74, v38
	v_fmac_f32_e32 v14, v74, v42
	v_fmac_f32_e32 v15, v74, v46
	v_fmac_f32_e32 v12, v74, v50
	v_fmac_f32_e32 v13, v74, v54
	v_fmac_f32_e32 v18, v75, v27
	v_fmac_f32_e32 v19, v75, v31
	v_fmac_f32_e32 v16, v75, v35
	v_fmac_f32_e32 v17, v75, v39
	v_fmac_f32_e32 v14, v75, v43
	v_fmac_f32_e32 v15, v75, v47
	v_fmac_f32_e32 v12, v75, v51
	v_fmac_f32_e32 v13, v75, v55
	v_fmac_f32_e32 v18, v76, v28
	v_fmac_f32_e32 v19, v76, v32
	v_fmac_f32_e32 v16, v76, v36
	v_fmac_f32_e32 v17, v76, v40
	v_fmac_f32_e32 v14, v76, v44
	v_fmac_f32_e32 v15, v76, v48
	v_fmac_f32_e32 v12, v76, v52
	v_fmac_f32_e32 v13, v76, v56
	v_fmac_f32_e32 v18, v77, v29
	v_fmac_f32_e32 v19, v77, v33
	v_fmac_f32_e32 v16, v77, v37
	v_fmac_f32_e32 v17, v77, v41
	v_fmac_f32_e32 v14, v77, v45
	v_fmac_f32_e32 v15, v77, v49
	v_fmac_f32_e32 v12, v77, v53
	v_fmac_f32_e32 v13, v77, v57
	global_load_dword v74, v[166:167], off
	v_lshl_add_u64 v[168:169], v[166:167], 0, v[158:159]
	v_lshl_add_u64 v[170:171], v[166:167], 0, v[160:161]
	v_lshl_add_u64 v[172:173], v[166:167], 0, v[162:163]
	global_load_dword v75, v[168:169], off
	global_load_dword v76, v[170:171], off
	global_load_dword v77, v[172:173], off
	v_lshl_add_u64 v[166:167], v[166:167], 0, v[164:165]
	ds_read_b128 v[26:29], v25
	ds_read_b128 v[30:33], v25 offset:4096
	ds_read_b128 v[34:37], v25 offset:8192
	ds_read_b128 v[38:41], v25 offset:12288
	ds_read_b128 v[42:45], v25 offset:16384
	ds_read_b128 v[46:49], v25 offset:20480
	ds_read_b128 v[50:53], v25 offset:24576
	ds_read_b128 v[54:57], v25 offset:28672
	v_add_u32_e32 v25, 16, v25
	s_waitcnt vmcnt(28)
	s_waitcnt lgkmcnt(0)
	v_fmac_f32_e32 v18, v78, v26
	v_fmac_f32_e32 v19, v78, v30
	v_fmac_f32_e32 v16, v78, v34
	v_fmac_f32_e32 v17, v78, v38
	v_fmac_f32_e32 v14, v78, v42
	v_fmac_f32_e32 v15, v78, v46
	v_fmac_f32_e32 v12, v78, v50
	v_fmac_f32_e32 v13, v78, v54
	v_fmac_f32_e32 v18, v79, v27
	v_fmac_f32_e32 v19, v79, v31
	v_fmac_f32_e32 v16, v79, v35
	v_fmac_f32_e32 v17, v79, v39
	v_fmac_f32_e32 v14, v79, v43
	v_fmac_f32_e32 v15, v79, v47
	v_fmac_f32_e32 v12, v79, v51
	v_fmac_f32_e32 v13, v79, v55
	v_fmac_f32_e32 v18, v80, v28
	v_fmac_f32_e32 v19, v80, v32
	v_fmac_f32_e32 v16, v80, v36
	v_fmac_f32_e32 v17, v80, v40
	v_fmac_f32_e32 v14, v80, v44
	v_fmac_f32_e32 v15, v80, v48
	v_fmac_f32_e32 v12, v80, v52
	v_fmac_f32_e32 v13, v80, v56
	v_fmac_f32_e32 v18, v81, v29
	v_fmac_f32_e32 v19, v81, v33
	v_fmac_f32_e32 v16, v81, v37
	v_fmac_f32_e32 v17, v81, v41
	v_fmac_f32_e32 v14, v81, v45
	v_fmac_f32_e32 v15, v81, v49
	v_fmac_f32_e32 v12, v81, v53
	v_fmac_f32_e32 v13, v81, v57
	global_load_dword v78, v[166:167], off
	v_lshl_add_u64 v[168:169], v[166:167], 0, v[158:159]
	v_lshl_add_u64 v[170:171], v[166:167], 0, v[160:161]
	v_lshl_add_u64 v[172:173], v[166:167], 0, v[162:163]
	global_load_dword v79, v[168:169], off
	global_load_dword v80, v[170:171], off
	global_load_dword v81, v[172:173], off
	v_lshl_add_u64 v[166:167], v[166:167], 0, v[164:165]
	ds_read_b128 v[26:29], v25
	ds_read_b128 v[30:33], v25 offset:4096
	ds_read_b128 v[34:37], v25 offset:8192
	ds_read_b128 v[38:41], v25 offset:12288
	ds_read_b128 v[42:45], v25 offset:16384
	ds_read_b128 v[46:49], v25 offset:20480
	ds_read_b128 v[50:53], v25 offset:24576
	ds_read_b128 v[54:57], v25 offset:28672
	v_add_u32_e32 v25, 16, v25
	s_waitcnt vmcnt(28)
	s_waitcnt lgkmcnt(0)
	v_fmac_f32_e32 v18, v82, v26
	v_fmac_f32_e32 v19, v82, v30
	v_fmac_f32_e32 v16, v82, v34
	v_fmac_f32_e32 v17, v82, v38
	v_fmac_f32_e32 v14, v82, v42
	v_fmac_f32_e32 v15, v82, v46
	v_fmac_f32_e32 v12, v82, v50
	v_fmac_f32_e32 v13, v82, v54
	v_fmac_f32_e32 v18, v83, v27
	v_fmac_f32_e32 v19, v83, v31
	v_fmac_f32_e32 v16, v83, v35
	v_fmac_f32_e32 v17, v83, v39
	v_fmac_f32_e32 v14, v83, v43
	v_fmac_f32_e32 v15, v83, v47
	v_fmac_f32_e32 v12, v83, v51
	v_fmac_f32_e32 v13, v83, v55
	v_fmac_f32_e32 v18, v84, v28
	v_fmac_f32_e32 v19, v84, v32
	v_fmac_f32_e32 v16, v84, v36
	v_fmac_f32_e32 v17, v84, v40
	v_fmac_f32_e32 v14, v84, v44
	v_fmac_f32_e32 v15, v84, v48
	v_fmac_f32_e32 v12, v84, v52
	v_fmac_f32_e32 v13, v84, v56
	v_fmac_f32_e32 v18, v85, v29
	v_fmac_f32_e32 v19, v85, v33
	v_fmac_f32_e32 v16, v85, v37
	v_fmac_f32_e32 v17, v85, v41
	v_fmac_f32_e32 v14, v85, v45
	v_fmac_f32_e32 v15, v85, v49
	v_fmac_f32_e32 v12, v85, v53
	v_fmac_f32_e32 v13, v85, v57
	global_load_dword v82, v[166:167], off
	v_lshl_add_u64 v[168:169], v[166:167], 0, v[158:159]
	v_lshl_add_u64 v[170:171], v[166:167], 0, v[160:161]
	v_lshl_add_u64 v[172:173], v[166:167], 0, v[162:163]
	global_load_dword v83, v[168:169], off
	global_load_dword v84, v[170:171], off
	global_load_dword v85, v[172:173], off
	v_lshl_add_u64 v[166:167], v[166:167], 0, v[164:165]
	ds_read_b128 v[26:29], v25
	ds_read_b128 v[30:33], v25 offset:4096
	ds_read_b128 v[34:37], v25 offset:8192
	ds_read_b128 v[38:41], v25 offset:12288
	ds_read_b128 v[42:45], v25 offset:16384
	ds_read_b128 v[46:49], v25 offset:20480
	ds_read_b128 v[50:53], v25 offset:24576
	ds_read_b128 v[54:57], v25 offset:28672
	v_add_u32_e32 v25, 16, v25
	s_waitcnt vmcnt(28)
	s_waitcnt lgkmcnt(0)
	v_fmac_f32_e32 v18, v86, v26
	v_fmac_f32_e32 v19, v86, v30
	v_fmac_f32_e32 v16, v86, v34
	v_fmac_f32_e32 v17, v86, v38
	v_fmac_f32_e32 v14, v86, v42
	v_fmac_f32_e32 v15, v86, v46
	v_fmac_f32_e32 v12, v86, v50
	v_fmac_f32_e32 v13, v86, v54
	v_fmac_f32_e32 v18, v87, v27
	v_fmac_f32_e32 v19, v87, v31
	v_fmac_f32_e32 v16, v87, v35
	v_fmac_f32_e32 v17, v87, v39
	v_fmac_f32_e32 v14, v87, v43
	v_fmac_f32_e32 v15, v87, v47
	v_fmac_f32_e32 v12, v87, v51
	v_fmac_f32_e32 v13, v87, v55
	v_fmac_f32_e32 v18, v88, v28
	v_fmac_f32_e32 v19, v88, v32
	v_fmac_f32_e32 v16, v88, v36
	v_fmac_f32_e32 v17, v88, v40
	v_fmac_f32_e32 v14, v88, v44
	v_fmac_f32_e32 v15, v88, v48
	v_fmac_f32_e32 v12, v88, v52
	v_fmac_f32_e32 v13, v88, v56
	v_fmac_f32_e32 v18, v89, v29
	v_fmac_f32_e32 v19, v89, v33
	v_fmac_f32_e32 v16, v89, v37
	v_fmac_f32_e32 v17, v89, v41
	v_fmac_f32_e32 v14, v89, v45
	v_fmac_f32_e32 v15, v89, v49
	v_fmac_f32_e32 v12, v89, v53
	v_fmac_f32_e32 v13, v89, v57
	global_load_dword v86, v[166:167], off
	v_lshl_add_u64 v[168:169], v[166:167], 0, v[158:159]
	v_lshl_add_u64 v[170:171], v[166:167], 0, v[160:161]
	v_lshl_add_u64 v[172:173], v[166:167], 0, v[162:163]
	global_load_dword v87, v[168:169], off
	global_load_dword v88, v[170:171], off
	global_load_dword v89, v[172:173], off
	v_lshl_add_u64 v[166:167], v[166:167], 0, v[164:165]
	ds_read_b128 v[26:29], v25
	ds_read_b128 v[30:33], v25 offset:4096
	ds_read_b128 v[34:37], v25 offset:8192
	ds_read_b128 v[38:41], v25 offset:12288
	ds_read_b128 v[42:45], v25 offset:16384
	ds_read_b128 v[46:49], v25 offset:20480
	ds_read_b128 v[50:53], v25 offset:24576
	ds_read_b128 v[54:57], v25 offset:28672
	v_add_u32_e32 v25, 16, v25
	s_waitcnt vmcnt(28)
	s_waitcnt lgkmcnt(0)
	v_fmac_f32_e32 v18, v90, v26
	v_fmac_f32_e32 v19, v90, v30
	v_fmac_f32_e32 v16, v90, v34
	v_fmac_f32_e32 v17, v90, v38
	v_fmac_f32_e32 v14, v90, v42
	v_fmac_f32_e32 v15, v90, v46
	v_fmac_f32_e32 v12, v90, v50
	v_fmac_f32_e32 v13, v90, v54
	v_fmac_f32_e32 v18, v91, v27
	v_fmac_f32_e32 v19, v91, v31
	v_fmac_f32_e32 v16, v91, v35
	v_fmac_f32_e32 v17, v91, v39
	v_fmac_f32_e32 v14, v91, v43
	v_fmac_f32_e32 v15, v91, v47
	v_fmac_f32_e32 v12, v91, v51
	v_fmac_f32_e32 v13, v91, v55
	v_fmac_f32_e32 v18, v92, v28
	v_fmac_f32_e32 v19, v92, v32
	v_fmac_f32_e32 v16, v92, v36
	v_fmac_f32_e32 v17, v92, v40
	v_fmac_f32_e32 v14, v92, v44
	v_fmac_f32_e32 v15, v92, v48
	v_fmac_f32_e32 v12, v92, v52
	v_fmac_f32_e32 v13, v92, v56
	v_fmac_f32_e32 v18, v93, v29
	v_fmac_f32_e32 v19, v93, v33
	v_fmac_f32_e32 v16, v93, v37
	v_fmac_f32_e32 v17, v93, v41
	v_fmac_f32_e32 v14, v93, v45
	v_fmac_f32_e32 v15, v93, v49
	v_fmac_f32_e32 v12, v93, v53
	v_fmac_f32_e32 v13, v93, v57
	global_load_dword v90, v[166:167], off
	v_lshl_add_u64 v[168:169], v[166:167], 0, v[158:159]
	v_lshl_add_u64 v[170:171], v[166:167], 0, v[160:161]
	v_lshl_add_u64 v[172:173], v[166:167], 0, v[162:163]
	global_load_dword v91, v[168:169], off
	global_load_dword v92, v[170:171], off
	global_load_dword v93, v[172:173], off
	v_lshl_add_u64 v[166:167], v[166:167], 0, v[164:165]
	ds_read_b128 v[26:29], v25
	ds_read_b128 v[30:33], v25 offset:4096
	ds_read_b128 v[34:37], v25 offset:8192
	ds_read_b128 v[38:41], v25 offset:12288
	ds_read_b128 v[42:45], v25 offset:16384
	ds_read_b128 v[46:49], v25 offset:20480
	ds_read_b128 v[50:53], v25 offset:24576
	ds_read_b128 v[54:57], v25 offset:28672
	v_add_u32_e32 v25, 16, v25
	s_waitcnt vmcnt(28)
	s_waitcnt lgkmcnt(0)
	v_fmac_f32_e32 v18, v94, v26
	v_fmac_f32_e32 v19, v94, v30
	v_fmac_f32_e32 v16, v94, v34
	v_fmac_f32_e32 v17, v94, v38
	v_fmac_f32_e32 v14, v94, v42
	v_fmac_f32_e32 v15, v94, v46
	v_fmac_f32_e32 v12, v94, v50
	v_fmac_f32_e32 v13, v94, v54
	v_fmac_f32_e32 v18, v95, v27
	v_fmac_f32_e32 v19, v95, v31
	v_fmac_f32_e32 v16, v95, v35
	v_fmac_f32_e32 v17, v95, v39
	v_fmac_f32_e32 v14, v95, v43
	v_fmac_f32_e32 v15, v95, v47
	v_fmac_f32_e32 v12, v95, v51
	v_fmac_f32_e32 v13, v95, v55
	v_fmac_f32_e32 v18, v96, v28
	v_fmac_f32_e32 v19, v96, v32
	v_fmac_f32_e32 v16, v96, v36
	v_fmac_f32_e32 v17, v96, v40
	v_fmac_f32_e32 v14, v96, v44
	v_fmac_f32_e32 v15, v96, v48
	v_fmac_f32_e32 v12, v96, v52
	v_fmac_f32_e32 v13, v96, v56
	v_fmac_f32_e32 v18, v97, v29
	v_fmac_f32_e32 v19, v97, v33
	v_fmac_f32_e32 v16, v97, v37
	v_fmac_f32_e32 v17, v97, v41
	v_fmac_f32_e32 v14, v97, v45
	v_fmac_f32_e32 v15, v97, v49
	v_fmac_f32_e32 v12, v97, v53
	v_fmac_f32_e32 v13, v97, v57
	global_load_dword v94, v[166:167], off
	v_lshl_add_u64 v[168:169], v[166:167], 0, v[158:159]
	v_lshl_add_u64 v[170:171], v[166:167], 0, v[160:161]
	v_lshl_add_u64 v[172:173], v[166:167], 0, v[162:163]
	global_load_dword v95, v[168:169], off
	global_load_dword v96, v[170:171], off
	global_load_dword v97, v[172:173], off
	v_lshl_add_u64 v[166:167], v[166:167], 0, v[164:165]
	s_sub_u32 s2, s2, 1
	s_cmp_lg_u32 s2, 0
	s_cbranch_scc1 .Lada_loop
	ds_read_b128 v[26:29], v25
	ds_read_b128 v[30:33], v25 offset:4096
	ds_read_b128 v[34:37], v25 offset:8192
	ds_read_b128 v[38:41], v25 offset:12288
	ds_read_b128 v[42:45], v25 offset:16384
	ds_read_b128 v[46:49], v25 offset:20480
	ds_read_b128 v[50:53], v25 offset:24576
	ds_read_b128 v[54:57], v25 offset:28672
	v_add_u32_e32 v25, 16, v25
	s_waitcnt vmcnt(28)
	s_waitcnt lgkmcnt(0)
	v_fmac_f32_e32 v18, v66, v26
	v_fmac_f32_e32 v19, v66, v30
	v_fmac_f32_e32 v16, v66, v34
	v_fmac_f32_e32 v17, v66, v38
	v_fmac_f32_e32 v14, v66, v42
	v_fmac_f32_e32 v15, v66, v46
	v_fmac_f32_e32 v12, v66, v50
	v_fmac_f32_e32 v13, v66, v54
	v_fmac_f32_e32 v18, v67, v27
	v_fmac_f32_e32 v19, v67, v31
	v_fmac_f32_e32 v16, v67, v35
	v_fmac_f32_e32 v17, v67, v39
	v_fmac_f32_e32 v14, v67, v43
	v_fmac_f32_e32 v15, v67, v47
	v_fmac_f32_e32 v12, v67, v51
	v_fmac_f32_e32 v13, v67, v55
	v_fmac_f32_e32 v18, v68, v28
	v_fmac_f32_e32 v19, v68, v32
	v_fmac_f32_e32 v16, v68, v36
	v_fmac_f32_e32 v17, v68, v40
	v_fmac_f32_e32 v14, v68, v44
	v_fmac_f32_e32 v15, v68, v48
	v_fmac_f32_e32 v12, v68, v52
	v_fmac_f32_e32 v13, v68, v56
	v_fmac_f32_e32 v18, v69, v29
	v_fmac_f32_e32 v19, v69, v33
	v_fmac_f32_e32 v16, v69, v37
	v_fmac_f32_e32 v17, v69, v41
	v_fmac_f32_e32 v14, v69, v45
	v_fmac_f32_e32 v15, v69, v49
	v_fmac_f32_e32 v12, v69, v53
	v_fmac_f32_e32 v13, v69, v57
	ds_read_b128 v[26:29], v25
	ds_read_b128 v[30:33], v25 offset:4096
	ds_read_b128 v[34:37], v25 offset:8192
	ds_read_b128 v[38:41], v25 offset:12288
	ds_read_b128 v[42:45], v25 offset:16384
	ds_read_b128 v[46:49], v25 offset:20480
	ds_read_b128 v[50:53], v25 offset:24576
	ds_read_b128 v[54:57], v25 offset:28672
	v_add_u32_e32 v25, 16, v25
	s_waitcnt vmcnt(24)
	s_waitcnt lgkmcnt(0)
	v_fmac_f32_e32 v18, v70, v26
	v_fmac_f32_e32 v19, v70, v30
	v_fmac_f32_e32 v16, v70, v34
	v_fmac_f32_e32 v17, v70, v38
	v_fmac_f32_e32 v14, v70, v42
	v_fmac_f32_e32 v15, v70, v46
	v_fmac_f32_e32 v12, v70, v50
	v_fmac_f32_e32 v13, v70, v54
	v_fmac_f32_e32 v18, v71, v27
	v_fmac_f32_e32 v19, v71, v31
	v_fmac_f32_e32 v16, v71, v35
	v_fmac_f32_e32 v17, v71, v39
	v_fmac_f32_e32 v14, v71, v43
	v_fmac_f32_e32 v15, v71, v47
	v_fmac_f32_e32 v12, v71, v51
	v_fmac_f32_e32 v13, v71, v55
	v_fmac_f32_e32 v18, v72, v28
	v_fmac_f32_e32 v19, v72, v32
	v_fmac_f32_e32 v16, v72, v36
	v_fmac_f32_e32 v17, v72, v40
	v_fmac_f32_e32 v14, v72, v44
	v_fmac_f32_e32 v15, v72, v48
	v_fmac_f32_e32 v12, v72, v52
	v_fmac_f32_e32 v13, v72, v56
	v_fmac_f32_e32 v18, v73, v29
	v_fmac_f32_e32 v19, v73, v33
	v_fmac_f32_e32 v16, v73, v37
	v_fmac_f32_e32 v17, v73, v41
	v_fmac_f32_e32 v14, v73, v45
	v_fmac_f32_e32 v15, v73, v49
	v_fmac_f32_e32 v12, v73, v53
	v_fmac_f32_e32 v13, v73, v57
	ds_read_b128 v[26:29], v25
	ds_read_b128 v[30:33], v25 offset:4096
	ds_read_b128 v[34:37], v25 offset:8192
	ds_read_b128 v[38:41], v25 offset:12288
	ds_read_b128 v[42:45], v25 offset:16384
	ds_read_b128 v[46:49], v25 offset:20480
	ds_read_b128 v[50:53], v25 offset:24576
	ds_read_b128 v[54:57], v25 offset:28672
	v_add_u32_e32 v25, 16, v25
	s_waitcnt vmcnt(20)
	s_waitcnt lgkmcnt(0)
	v_fmac_f32_e32 v18, v74, v26
	v_fmac_f32_e32 v19, v74, v30
	v_fmac_f32_e32 v16, v74, v34
	v_fmac_f32_e32 v17, v74, v38
	v_fmac_f32_e32 v14, v74, v42
	v_fmac_f32_e32 v15, v74, v46
	v_fmac_f32_e32 v12, v74, v50
	v_fmac_f32_e32 v13, v74, v54
	v_fmac_f32_e32 v18, v75, v27
	v_fmac_f32_e32 v19, v75, v31
	v_fmac_f32_e32 v16, v75, v35
	v_fmac_f32_e32 v17, v75, v39
	v_fmac_f32_e32 v14, v75, v43
	v_fmac_f32_e32 v15, v75, v47
	v_fmac_f32_e32 v12, v75, v51
	v_fmac_f32_e32 v13, v75, v55
	v_fmac_f32_e32 v18, v76, v28
	v_fmac_f32_e32 v19, v76, v32
	v_fmac_f32_e32 v16, v76, v36
	v_fmac_f32_e32 v17, v76, v40
	v_fmac_f32_e32 v14, v76, v44
	v_fmac_f32_e32 v15, v76, v48
	v_fmac_f32_e32 v12, v76, v52
	v_fmac_f32_e32 v13, v76, v56
	v_fmac_f32_e32 v18, v77, v29
	v_fmac_f32_e32 v19, v77, v33
	v_fmac_f32_e32 v16, v77, v37
	v_fmac_f32_e32 v17, v77, v41
	v_fmac_f32_e32 v14, v77, v45
	v_fmac_f32_e32 v15, v77, v49
	v_fmac_f32_e32 v12, v77, v53
	v_fmac_f32_e32 v13, v77, v57
	ds_read_b128 v[26:29], v25
	ds_read_b128 v[30:33], v25 offset:4096
	ds_read_b128 v[34:37], v25 offset:8192
	ds_read_b128 v[38:41], v25 offset:12288
	ds_read_b128 v[42:45], v25 offset:16384
	ds_read_b128 v[46:49], v25 offset:20480
	ds_read_b128 v[50:53], v25 offset:24576
	ds_read_b128 v[54:57], v25 offset:28672
	v_add_u32_e32 v25, 16, v25
	s_waitcnt vmcnt(16)
	s_waitcnt lgkmcnt(0)
	v_fmac_f32_e32 v18, v78, v26
	v_fmac_f32_e32 v19, v78, v30
	v_fmac_f32_e32 v16, v78, v34
	v_fmac_f32_e32 v17, v78, v38
	v_fmac_f32_e32 v14, v78, v42
	v_fmac_f32_e32 v15, v78, v46
	v_fmac_f32_e32 v12, v78, v50
	v_fmac_f32_e32 v13, v78, v54
	v_fmac_f32_e32 v18, v79, v27
	v_fmac_f32_e32 v19, v79, v31
	v_fmac_f32_e32 v16, v79, v35
	v_fmac_f32_e32 v17, v79, v39
	v_fmac_f32_e32 v14, v79, v43
	v_fmac_f32_e32 v15, v79, v47
	v_fmac_f32_e32 v12, v79, v51
	v_fmac_f32_e32 v13, v79, v55
	v_fmac_f32_e32 v18, v80, v28
	v_fmac_f32_e32 v19, v80, v32
	v_fmac_f32_e32 v16, v80, v36
	v_fmac_f32_e32 v17, v80, v40
	v_fmac_f32_e32 v14, v80, v44
	v_fmac_f32_e32 v15, v80, v48
	v_fmac_f32_e32 v12, v80, v52
	v_fmac_f32_e32 v13, v80, v56
	v_fmac_f32_e32 v18, v81, v29
	v_fmac_f32_e32 v19, v81, v33
	v_fmac_f32_e32 v16, v81, v37
	v_fmac_f32_e32 v17, v81, v41
	v_fmac_f32_e32 v14, v81, v45
	v_fmac_f32_e32 v15, v81, v49
	v_fmac_f32_e32 v12, v81, v53
	v_fmac_f32_e32 v13, v81, v57
	ds_read_b128 v[26:29], v25
	ds_read_b128 v[30:33], v25 offset:4096
	ds_read_b128 v[34:37], v25 offset:8192
	ds_read_b128 v[38:41], v25 offset:12288
	ds_read_b128 v[42:45], v25 offset:16384
	ds_read_b128 v[46:49], v25 offset:20480
	ds_read_b128 v[50:53], v25 offset:24576
	ds_read_b128 v[54:57], v25 offset:28672
	v_add_u32_e32 v25, 16, v25
	s_waitcnt vmcnt(12)
	s_waitcnt lgkmcnt(0)
	v_fmac_f32_e32 v18, v82, v26
	v_fmac_f32_e32 v19, v82, v30
	v_fmac_f32_e32 v16, v82, v34
	v_fmac_f32_e32 v17, v82, v38
	v_fmac_f32_e32 v14, v82, v42
	v_fmac_f32_e32 v15, v82, v46
	v_fmac_f32_e32 v12, v82, v50
	v_fmac_f32_e32 v13, v82, v54
	v_fmac_f32_e32 v18, v83, v27
	v_fmac_f32_e32 v19, v83, v31
	v_fmac_f32_e32 v16, v83, v35
	v_fmac_f32_e32 v17, v83, v39
	v_fmac_f32_e32 v14, v83, v43
	v_fmac_f32_e32 v15, v83, v47
	v_fmac_f32_e32 v12, v83, v51
	v_fmac_f32_e32 v13, v83, v55
	v_fmac_f32_e32 v18, v84, v28
	v_fmac_f32_e32 v19, v84, v32
	v_fmac_f32_e32 v16, v84, v36
	v_fmac_f32_e32 v17, v84, v40
	v_fmac_f32_e32 v14, v84, v44
	v_fmac_f32_e32 v15, v84, v48
	v_fmac_f32_e32 v12, v84, v52
	v_fmac_f32_e32 v13, v84, v56
	v_fmac_f32_e32 v18, v85, v29
	v_fmac_f32_e32 v19, v85, v33
	v_fmac_f32_e32 v16, v85, v37
	v_fmac_f32_e32 v17, v85, v41
	v_fmac_f32_e32 v14, v85, v45
	v_fmac_f32_e32 v15, v85, v49
	v_fmac_f32_e32 v12, v85, v53
	v_fmac_f32_e32 v13, v85, v57
	ds_read_b128 v[26:29], v25
	ds_read_b128 v[30:33], v25 offset:4096
	ds_read_b128 v[34:37], v25 offset:8192
	ds_read_b128 v[38:41], v25 offset:12288
	ds_read_b128 v[42:45], v25 offset:16384
	ds_read_b128 v[46:49], v25 offset:20480
	ds_read_b128 v[50:53], v25 offset:24576
	ds_read_b128 v[54:57], v25 offset:28672
	v_add_u32_e32 v25, 16, v25
	s_waitcnt vmcnt(8)
	s_waitcnt lgkmcnt(0)
	v_fmac_f32_e32 v18, v86, v26
	v_fmac_f32_e32 v19, v86, v30
	v_fmac_f32_e32 v16, v86, v34
	v_fmac_f32_e32 v17, v86, v38
	v_fmac_f32_e32 v14, v86, v42
	v_fmac_f32_e32 v15, v86, v46
	v_fmac_f32_e32 v12, v86, v50
	v_fmac_f32_e32 v13, v86, v54
	v_fmac_f32_e32 v18, v87, v27
	v_fmac_f32_e32 v19, v87, v31
	v_fmac_f32_e32 v16, v87, v35
	v_fmac_f32_e32 v17, v87, v39
	v_fmac_f32_e32 v14, v87, v43
	v_fmac_f32_e32 v15, v87, v47
	v_fmac_f32_e32 v12, v87, v51
	v_fmac_f32_e32 v13, v87, v55
	v_fmac_f32_e32 v18, v88, v28
	v_fmac_f32_e32 v19, v88, v32
	v_fmac_f32_e32 v16, v88, v36
	v_fmac_f32_e32 v17, v88, v40
	v_fmac_f32_e32 v14, v88, v44
	v_fmac_f32_e32 v15, v88, v48
	v_fmac_f32_e32 v12, v88, v52
	v_fmac_f32_e32 v13, v88, v56
	v_fmac_f32_e32 v18, v89, v29
	v_fmac_f32_e32 v19, v89, v33
	v_fmac_f32_e32 v16, v89, v37
	v_fmac_f32_e32 v17, v89, v41
	v_fmac_f32_e32 v14, v89, v45
	v_fmac_f32_e32 v15, v89, v49
	v_fmac_f32_e32 v12, v89, v53
	v_fmac_f32_e32 v13, v89, v57
	ds_read_b128 v[26:29], v25
	ds_read_b128 v[30:33], v25 offset:4096
	ds_read_b128 v[34:37], v25 offset:8192
	ds_read_b128 v[38:41], v25 offset:12288
	ds_read_b128 v[42:45], v25 offset:16384
	ds_read_b128 v[46:49], v25 offset:20480
	ds_read_b128 v[50:53], v25 offset:24576
	ds_read_b128 v[54:57], v25 offset:28672
	v_add_u32_e32 v25, 16, v25
	s_waitcnt vmcnt(4)
	s_waitcnt lgkmcnt(0)
	v_fmac_f32_e32 v18, v90, v26
	v_fmac_f32_e32 v19, v90, v30
	v_fmac_f32_e32 v16, v90, v34
	v_fmac_f32_e32 v17, v90, v38
	v_fmac_f32_e32 v14, v90, v42
	v_fmac_f32_e32 v15, v90, v46
	v_fmac_f32_e32 v12, v90, v50
	v_fmac_f32_e32 v13, v90, v54
	v_fmac_f32_e32 v18, v91, v27
	v_fmac_f32_e32 v19, v91, v31
	v_fmac_f32_e32 v16, v91, v35
	v_fmac_f32_e32 v17, v91, v39
	v_fmac_f32_e32 v14, v91, v43
	v_fmac_f32_e32 v15, v91, v47
	v_fmac_f32_e32 v12, v91, v51
	v_fmac_f32_e32 v13, v91, v55
	v_fmac_f32_e32 v18, v92, v28
	v_fmac_f32_e32 v19, v92, v32
	v_fmac_f32_e32 v16, v92, v36
	v_fmac_f32_e32 v17, v92, v40
	v_fmac_f32_e32 v14, v92, v44
	v_fmac_f32_e32 v15, v92, v48
	v_fmac_f32_e32 v12, v92, v52
	v_fmac_f32_e32 v13, v92, v56
	v_fmac_f32_e32 v18, v93, v29
	v_fmac_f32_e32 v19, v93, v33
	v_fmac_f32_e32 v16, v93, v37
	v_fmac_f32_e32 v17, v93, v41
	v_fmac_f32_e32 v14, v93, v45
	v_fmac_f32_e32 v15, v93, v49
	v_fmac_f32_e32 v12, v93, v53
	v_fmac_f32_e32 v13, v93, v57
	ds_read_b128 v[26:29], v25
	ds_read_b128 v[30:33], v25 offset:4096
	ds_read_b128 v[34:37], v25 offset:8192
	ds_read_b128 v[38:41], v25 offset:12288
	ds_read_b128 v[42:45], v25 offset:16384
	ds_read_b128 v[46:49], v25 offset:20480
	ds_read_b128 v[50:53], v25 offset:24576
	ds_read_b128 v[54:57], v25 offset:28672
	v_add_u32_e32 v25, 16, v25
	s_waitcnt vmcnt(0)
	s_waitcnt lgkmcnt(0)
	v_fmac_f32_e32 v18, v94, v26
	v_fmac_f32_e32 v19, v94, v30
	v_fmac_f32_e32 v16, v94, v34
	v_fmac_f32_e32 v17, v94, v38
	v_fmac_f32_e32 v14, v94, v42
	v_fmac_f32_e32 v15, v94, v46
	v_fmac_f32_e32 v12, v94, v50
	v_fmac_f32_e32 v13, v94, v54
	v_fmac_f32_e32 v18, v95, v27
	v_fmac_f32_e32 v19, v95, v31
	v_fmac_f32_e32 v16, v95, v35
	v_fmac_f32_e32 v17, v95, v39
	v_fmac_f32_e32 v14, v95, v43
	v_fmac_f32_e32 v15, v95, v47
	v_fmac_f32_e32 v12, v95, v51
	v_fmac_f32_e32 v13, v95, v55
	v_fmac_f32_e32 v18, v96, v28
	v_fmac_f32_e32 v19, v96, v32
	v_fmac_f32_e32 v16, v96, v36
	v_fmac_f32_e32 v17, v96, v40
	v_fmac_f32_e32 v14, v96, v44
	v_fmac_f32_e32 v15, v96, v48
	v_fmac_f32_e32 v12, v96, v52
	v_fmac_f32_e32 v13, v96, v56
	v_fmac_f32_e32 v18, v97, v29
	v_fmac_f32_e32 v19, v97, v33
	v_fmac_f32_e32 v16, v97, v37
	v_fmac_f32_e32 v17, v97, v41
	v_fmac_f32_e32 v14, v97, v45
	v_fmac_f32_e32 v15, v97, v49
	v_fmac_f32_e32 v12, v97, v53
	v_fmac_f32_e32 v13, v97, v57
	ds_write2st64_b32 v21, v18, v19 offset0:128 offset1:129
	ds_write2st64_b32 v21, v16, v17 offset0:130 offset1:131
	ds_write2st64_b32 v21, v14, v15 offset0:132 offset1:133
	ds_write2st64_b32 v21, v12, v13 offset0:134 offset1:135
	s_waitcnt lgkmcnt(0)
	s_barrier
	s_and_saveexec_b64 s[2:3], s[40:41]
	s_cbranch_execz .LBB0_533
	s_mul_i32 s5, s4, 0xc00
	v_readlane_b32 s44, v252, 15
	s_lshl_b32 s7, s4, 3
	v_add_u32_e32 v10, s5, v8
	v_readlane_b32 s56, v252, 27
	v_readlane_b32 s57, v252, 28
	v_readlane_b32 s4, v255, 10
	v_ashrrev_i32_e32 v11, 31, v10
	v_readlane_b32 s52, v252, 23
	v_readlane_b32 s53, v252, 24
	v_readlane_b32 s56, v254, 57
	v_readlane_b32 s5, v255, 11
	v_readlane_b32 s57, v254, 58
	v_lshl_add_u64 v[10:11], v[10:11], 2, s[52:53]
	v_lshl_add_u64 v[8:9], v[8:9], 2, s[4:5]
	s_mov_b64 s[4:5], 0
	v_mov_b32_e32 v12, v24
	v_mov_b32_e32 v13, v2
	v_readlane_b32 s45, v252, 16
	v_readlane_b32 s46, v252, 17
	v_readlane_b32 s47, v252, 18
	v_readlane_b32 s48, v252, 19
	v_readlane_b32 s49, v252, 20
	v_readlane_b32 s50, v252, 21
	v_readlane_b32 s51, v252, 22
	v_readlane_b32 s54, v252, 25
	v_readlane_b32 s55, v252, 26
	v_readlane_b32 s58, v252, 29
	v_readlane_b32 s59, v252, 30
